# c17 + ssd_out item prologue: the 8 image-staging loads issued as one batch into dead accumulator registers (were load-wait-ds_write serialised)
# speedup vs baseline: 1.0022x; 1.0022x over previous
; #define LAS __attribute__((address_space(3)))
; __device__ __forceinline__ float shfl_lane(float v, int srclane) { return __int_as_float(__builtin_amdgcn_ds_bpermute(srclane << 2, __float_as_int(v))); }
; __device__ __forceinline__ void ssd_tables(const Frame& F, const float* DT, int t0, int head, float A0, float A1, LAS float* tab) {
;     const int L = F.lane; const float* dp = DT + (size_t)(t0 + 2 * L) * 128 + head;
;     const float a0 = dp[0], a1 = dp[128], b0 = dp[64], b1 = dp[128 + 64];
;     float sa = a0 + a1, sb = b0 + b1, ia = sa, ib = sb;
; #pragma unroll
;     for (int o = 1; o < 64; o <<= 1) { const float xa = shfl_lane(ia, (L - o) & 63), xb = shfl_lane(ib, (L - o) & 63); if (L >= o) { ia += xa; ib += xb; } }
;     const float totb = shfl_lane(ib, 63);
;     const float ea = ia - sa, eb = ib - sb;
;     tab[2 * L] = A0 * (ea + a0); tab[2 * L + 1] = A0 * (ea + a0 + a1);
;     tab[128 + 2 * L] = A1 * (totb - eb); tab[128 + 2 * L + 1] = A1 * (totb - eb - b0);
;     tab[256 + 2 * L] = a0; tab[256 + 2 * L + 1] = a1; tab[384 + 2 * L] = b0; tab[384 + 2 * L + 1] = b1;
; }
; __device__ __forceinline__ void p_ssd_out(const Frame& F0, const bf16* XT, const bf16* BMt, const bf16* CMt, const float* DT, const float* alog, const float* dskip, const bf16* ST,
;                                           const bf16* ZS, const float* ng, bf16* Y) {
;     ...
;         const int c = it >> 3, g = it & 7, head = g * 8 + F.wave, t0 = c * 128;
;         stage_img(F, BMt + (size_t)t0 * 1024 + g * 128, 1024, imgB);
;         stage_img(F, CMt + (size_t)t0 * 1024 + g * 128, 1024, imgC);
;         const float A0 = -1.4426950408889634f * __expf(alog[head]), A1 = -1.4426950408889634f * __expf(alog[64 + head]), dsk = dskip[head];
;         ssd_tables(F, DT, t0, head, A0, A1, tab);
;         __syncthreads();
.LBB0_444:
	s_ashr_i32 s18, s2, 3
	s_and_b32 s17, s2, 7
	s_lshl_b32 s24, s18, 7
	s_lshl_b32 s0, s17, 3
	s_ashr_i32 s25, s24, 31
	s_add_i32 s16, s0, s33
	s_lshl_b64 s[0:1], s[24:25], 11
	s_add_u32 s19, s8, s0
	s_addc_u32 s21, s9, s1
	s_lshl_b32 s17, s17, 8
	s_add_u32 s20, s19, s17
	s_addc_u32 s21, s21, 0
	v_lshl_add_u64 v[2:3], s[20:21], 0, v[168:169]
	v_mov_b32_e32 v177, v131
	v_lshl_add_u64 v[2:3], v[2:3], 0, v[176:177]
	global_load_dwordx4 v[2:5], v[2:3], off
	v_readlane_b32 s19, v251, 11
	s_add_u32 s0, s19, s0
	v_readlane_b32 s19, v251, 12
	s_addc_u32 s1, s19, s1
	s_add_u32 s0, s0, s17
	s_addc_u32 s1, s1, 0
	v_lshl_add_u64 v[16:17], s[20:21], 0, v[170:171]
	v_lshl_add_u64 v[16:17], v[16:17], 0, v[176:177]
	global_load_dwordx4 v[16:19], v[16:17], off
	v_lshl_add_u64 v[20:21], s[20:21], 0, v[172:173]
	v_lshl_add_u64 v[20:21], v[20:21], 0, v[176:177]
	global_load_dwordx4 v[20:23], v[20:21], off
	v_lshl_add_u64 v[24:25], s[20:21], 0, v[174:175]
	v_lshl_add_u64 v[24:25], v[24:25], 0, v[176:177]
	global_load_dwordx4 v[24:27], v[24:25], off
	v_lshl_add_u64 v[28:29], s[0:1], 0, v[168:169]
	v_lshl_add_u64 v[28:29], v[28:29], 0, v[176:177]
	global_load_dwordx4 v[28:31], v[28:29], off
	v_lshl_add_u64 v[32:33], s[0:1], 0, v[170:171]
	v_lshl_add_u64 v[32:33], v[32:33], 0, v[176:177]
	global_load_dwordx4 v[32:35], v[32:33], off
	v_lshl_add_u64 v[36:37], s[0:1], 0, v[172:173]
	v_lshl_add_u64 v[36:37], v[36:37], 0, v[176:177]
	global_load_dwordx4 v[36:39], v[36:37], off
	v_lshl_add_u64 v[40:41], s[0:1], 0, v[174:175]
	v_lshl_add_u64 v[40:41], v[40:41], 0, v[176:177]
	global_load_dwordx4 v[40:43], v[40:41], off
	s_ashr_i32 s17, s16, 31
	v_readlane_b32 s64, v250, 21
	v_readlane_b32 s78, v250, 35
	v_readlane_b32 s79, v250, 36
	v_readlane_b32 s65, v250, 22
	v_readlane_b32 s66, v250, 23
	v_readlane_b32 s67, v250, 24
	v_readlane_b32 s68, v250, 25
	v_readlane_b32 s69, v250, 26
	v_readlane_b32 s70, v250, 27
	v_readlane_b32 s71, v250, 28
	v_readlane_b32 s72, v250, 29
	v_readlane_b32 s73, v250, 30
	v_readlane_b32 s74, v250, 31
	v_readlane_b32 s75, v250, 32
	v_readlane_b32 s76, v250, 33
	v_readlane_b32 s77, v250, 34
	v_or_b32_e32 v6, s24, v189
	v_ashrrev_i32_e32 v7, 31, v6
	v_lshlrev_b64 v[6:7], 9, v[6:7]
	v_readlane_b32 s22, v254, 31
	v_readlane_b32 s23, v254, 32
	s_lshl_b64 s[0:1], s[16:17], 2
	s_add_u32 s20, s78, s0
	s_addc_u32 s21, s79, s1
	global_load_dword v1, v131, s[20:21]
	v_readlane_b32 s64, v250, 37
	v_readlane_b32 s65, v250, 38
	v_readlane_b32 s68, v250, 41
	v_readlane_b32 s69, v250, 42
	v_readlane_b32 s68, v254, 35
	v_readlane_b32 s69, v254, 36
	v_readlane_b32 s66, v250, 39
	v_readlane_b32 s67, v250, 40
	v_readlane_b32 s70, v250, 43
	v_readlane_b32 s71, v250, 44
	v_readlane_b32 s72, v250, 45
	v_readlane_b32 s73, v250, 46
	v_readlane_b32 s74, v250, 47
	v_readlane_b32 s75, v250, 48
	v_readlane_b32 s76, v250, 49
	v_readlane_b32 s77, v250, 50
	v_readlane_b32 s78, v250, 51
	v_readlane_b32 s79, v250, 52
	s_waitcnt vmcnt(8)
	ds_write_b128 v220, v[2:5]
	s_waitcnt vmcnt(7)
	ds_write_b128 v221, v[16:19]
	s_waitcnt vmcnt(6)
	ds_write_b128 v222, v[20:23]
	s_waitcnt vmcnt(5)
	ds_write_b128 v223, v[24:27]
	s_waitcnt vmcnt(4)
	ds_write_b128 v220, v[28:31] offset:34816
	s_waitcnt vmcnt(3)
	ds_write_b128 v221, v[32:35] offset:34816
	s_waitcnt vmcnt(2)
	ds_write_b128 v222, v[36:39] offset:34816
	s_waitcnt vmcnt(1)
	ds_write_b128 v223, v[40:43] offset:34816
	s_waitcnt vmcnt(0)
	v_mul_f32_e32 v1, 0x3fb8aa3b, v1
	v_exp_f32_e32 v1, v1
	s_nop 0
	v_mul_f32_e32 v2, 0xbfb8aa3b, v1
	global_load_dword v1, v131, s[20:21] offset:256
	s_add_u32 s20, s64, s0
	s_addc_u32 s21, s65, s1
	global_load_dword v178, v131, s[20:21]
	v_readlane_b32 s20, v251, 13
	v_readlane_b32 s21, v251, 14
	s_mov_b32 s65, 0
	s_movk_i32 s64, 0x90
	v_lshl_add_u64 v[6:7], s[20:21], 0, v[6:7]
	v_lshl_add_u64 v[6:7], v[6:7], 0, s[0:1]
	global_load_dword v8, v[6:7], off
	global_load_dword v9, v[6:7], off offset:512
	global_load_dword v10, v[6:7], off offset:256
	global_load_dword v11, v[6:7], off offset:768
	s_waitcnt vmcnt(5)
	v_mul_f32_e32 v1, 0x3fb8aa3b, v1
	v_exp_f32_e32 v1, v1
	s_waitcnt vmcnt(4)
	v_mov_b32_e32 v179, v178
	v_mul_f32_e32 v4, 0xbfb8aa3b, v1
	s_waitcnt vmcnt(2)
	v_add_f32_e32 v1, v8, v9
	ds_bpermute_b32 v5, v193, v1
	s_waitcnt vmcnt(0)
	v_add_f32_e32 v3, v10, v11
	ds_bpermute_b32 v6, v193, v3
	s_waitcnt lgkmcnt(1)
	v_add_f32_e32 v5, v1, v5
	v_cndmask_b32_e64 v5, v5, v1, s[36:37]
	s_waitcnt lgkmcnt(0)
	v_add_f32_e32 v6, v3, v6
	v_cndmask_b32_e64 v6, v6, v3, s[36:37]
	ds_bpermute_b32 v7, v214, v5
	ds_bpermute_b32 v12, v214, v6
	s_waitcnt lgkmcnt(1)
	v_add_f32_e32 v7, v5, v7
	s_waitcnt lgkmcnt(0)
	v_add_f32_e32 v12, v6, v12
	v_cndmask_b32_e64 v5, v7, v5, s[38:39]
	v_cndmask_b32_e64 v6, v12, v6, s[38:39]
	ds_bpermute_b32 v7, v215, v5
	ds_bpermute_b32 v12, v215, v6
	s_waitcnt lgkmcnt(1)
	v_add_f32_e32 v7, v5, v7
	s_waitcnt lgkmcnt(0)
	v_add_f32_e32 v12, v6, v12
	v_cndmask_b32_e64 v5, v7, v5, s[40:41]
	v_cndmask_b32_e64 v6, v12, v6, s[40:41]
	ds_bpermute_b32 v7, v216, v5
	ds_bpermute_b32 v12, v216, v6
	s_waitcnt lgkmcnt(1)
	v_add_f32_e32 v7, v5, v7
	s_waitcnt lgkmcnt(0)
	v_add_f32_e32 v12, v6, v12
	v_cndmask_b32_e64 v5, v7, v5, s[42:43]
	v_cndmask_b32_e64 v6, v12, v6, s[42:43]
	ds_bpermute_b32 v7, v217, v5
	ds_bpermute_b32 v12, v217, v6
	s_waitcnt lgkmcnt(1)
	v_add_f32_e32 v7, v5, v7
	s_waitcnt lgkmcnt(0)
	v_add_f32_e32 v12, v6, v12
	v_cndmask_b32_e64 v5, v7, v5, s[44:45]
	v_cndmask_b32_e64 v6, v12, v6, s[44:45]
	ds_bpermute_b32 v7, v218, v5
	ds_bpermute_b32 v12, v218, v6
	s_waitcnt lgkmcnt(1)
	v_add_f32_e32 v7, v5, v7
	s_waitcnt lgkmcnt(0)
	v_add_f32_e32 v12, v6, v12
	v_cndmask_b32_e64 v5, v7, v5, s[46:47]
	v_cndmask_b32_e64 v6, v12, v6, s[46:47]
	v_sub_f32_e32 v1, v5, v1
	v_readlane_b32 s0, v6, 63
	v_sub_f32_e32 v5, v6, v3
	v_add_f32_e32 v6, v8, v1
	v_add_f32_e32 v7, v9, v6
	v_pk_mul_f32 v[2:3], v[2:3], v[6:7] op_sel_hi:[0,1]
	v_sub_f32_e32 v6, s0, v5
	s_lshl_b32 s0, s18, 6
	s_add_i32 s0, s16, s0
	s_ashr_i32 s1, s0, 31
	s_lshl_b64 s[0:1], s[0:1], 14
	s_add_u32 s26, s68, s0
	s_addc_u32 s27, s69, s1
	s_lshl_b32 s0, s18, 1
	s_ashr_i32 s1, s0, 31
	s_lshl_b64 s[0:1], s[0:1], 20
	v_readlane_b32 s18, v251, 15
	v_readlane_b32 s19, v251, 16
	s_add_u32 s18, s18, s0
	s_addc_u32 s19, s19, s1
	s_lshl_b64 s[0:1], s[16:17], 14
	s_add_u32 s0, s18, s0
	s_addc_u32 s1, s19, s1
	s_add_u32 s28, s0, 0x1000
	s_addc_u32 s29, s1, 0
	s_lshl_b32 s16, s16, 6
	s_ashr_i32 s17, s16, 31
	s_lshl_b64 s[18:19], s[16:17], 1
	s_add_u32 s30, s52, s18
	s_addc_u32 s31, s53, s19
	s_lshl_b64 s[16:17], s[16:17], 2
	s_add_u32 s54, s66, s16
	s_addc_u32 s55, s67, s17
	s_add_u32 s56, s22, s18
	s_addc_u32 s57, s23, s19
	s_add_u32 s60, s0, 0x3000
	s_addc_u32 s61, s1, 0
	s_add_u32 s16, s0, 0x101000
	s_addc_u32 s17, s1, 0
	v_sub_f32_e32 v7, v6, v10
	s_add_u32 s18, s0, 0x103000
	v_pk_mul_f32 v[4:5], v[4:5], v[6:7] op_sel_hi:[0,1]
	s_addc_u32 s19, s1, 0
	s_mov_b64 s[22:23], -1
	ds_write2st64_b64 v219, v[2:3], v[4:5] offset1:1
	ds_write2st64_b64 v219, v[8:9], v[10:11] offset0:2 offset1:3
	s_waitcnt lgkmcnt(0)
	s_barrier
; __device__ __forceinline__ void p_ssd_out(const Frame& F0, const bf16* XT, const bf16* BMt, const bf16* CMt, const float* DT, const float* alog, const float* dskip, const bf16* ST,
;                                           const bf16* ZS, const float* ng, bf16* Y) {
;     ...
;     for (int it = blockIdx.x; it < 64 * 8; it += F.G) {
;         const int c = it >> 3, g = it & 7, head = g * 8 + F.wave, t0 = c * 128;
;         stage_img(F, BMt + (size_t)t0 * 1024 + g * 128, 1024, imgB);
;         stage_img(F, CMt + (size_t)t0 * 1024 + g * 128, 1024, imgC);
;         const float A0 = -1.4426950408889634f * __expf(alog[head]), A1 = -1.4426950408889634f * __expf(alog[64 + head]), dsk = dskip[head];
;         ssd_tables(F, DT, t0, head, A0, A1, tab);
;         __syncthreads();
	s_branch .LBB0_446
